# GEMM4 epilogue: all 16 gate-row loads of a tile requested before the LDS transposition, row loop unrolled (was 4 loads per loop trip, each trip exposing a round trip)
# speedup vs baseline: 1.0045x; 1.0045x over previous
.LBB0_808:
	s_and_b32 s14, s36, 3
	v_mov_b32_e32 v62, v212
	s_and_b32 s15, s21, 0xffffff80
	s_lshl_b32 s14, s14, 9
	s_lshl_b32 s1, s1, 17
	s_add_u32 s16, s3, s1
	v_ashrrev_i32_e32 v26, 3, v62
	v_ashrrev_i32_e32 v27, 31, v26
	s_addc_u32 s17, s20, 0
	v_lshlrev_b64 v[2:3], 9, v[26:27]
	v_lshlrev_b32_e32 v4, 4, v62
	v_lshl_add_u64 v[2:3], s[16:17], 0, v[2:3]
	v_and_b32_e32 v66, 0x70, v4
	s_ashr_i32 s1, s0, 31
	v_lshl_add_u64 v[50:51], v[2:3], 0, v[66:67]
	s_lshl_b64 s[0:1], s[0:1], 11
	v_add_co_u32_e32 v54, vcc, s25, v50
	s_add_u32 s0, s8, s0
	s_nop 0
	v_addc_co_u32_e32 v55, vcc, 0, v51, vcc
	s_addc_u32 s1, s9, s1
	s_lshl_b32 s18, s38, 1
	v_add_co_u32_e32 v56, vcc, s26, v50
	s_add_u32 s0, s0, s18
	s_nop 0
	v_addc_co_u32_e32 v57, vcc, 0, v51, vcc
	s_addc_u32 s1, s1, 0
	v_lshlrev_b64 v[2:3], 11, v[26:27]
	v_add_co_u32_e32 v58, vcc, s27, v50
	v_lshl_add_u64 v[2:3], s[0:1], 0, v[2:3]
	s_nop 0
	v_addc_co_u32_e32 v59, vcc, 0, v51, vcc
	v_lshl_add_u64 v[52:53], v[2:3], 0, v[66:67]
	global_load_dwordx4 v[2:5], v[50:51], off
	global_load_dwordx4 v[6:9], v[54:55], off
	global_load_dwordx4 v[10:13], v[56:57], off
	global_load_dwordx4 v[14:17], v[58:59], off
	global_load_dwordx4 v[18:21], v[52:53], off
	v_add_co_u32_e32 v60, vcc, s28, v52
	v_mad_u64_u32 v[152:153], s[0:1], v26, s23, v[66:67]
	s_nop 0
	v_addc_co_u32_e32 v61, vcc, 0, v53, vcc
	global_load_dwordx4 v[22:25], v[60:61], off
	global_load_dwordx4 v[26:29], v[50:51], off offset:128
	global_load_dwordx4 v[30:33], v[54:55], off offset:128
	global_load_dwordx4 v[34:37], v[58:59], off offset:128
	global_load_dwordx4 v[72:75], v[54:55], off offset:256
	global_load_dwordx4 v[38:41], v[56:57], off offset:128
	global_load_dwordx4 v[76:79], v[56:57], off offset:256
	global_load_dwordx4 v[80:83], v[50:51], off offset:256
	global_load_dwordx4 v[42:45], v[52:53], off offset:128
	global_load_dwordx4 v[84:87], v[52:53], off offset:256
	global_load_dwordx4 v[88:91], v[58:59], off offset:256
	global_load_dwordx4 v[46:49], v[60:61], off offset:128
	global_load_dwordx4 v[92:95], v[60:61], off offset:256
	v_add_u32_e32 v153, 0x12000, v152
	s_waitcnt vmcnt(17)
	ds_write_b128 v152, v[2:5]
	s_waitcnt vmcnt(16)
	ds_write_b128 v152, v[6:9] offset:9216
	s_waitcnt vmcnt(15)
	ds_write_b128 v152, v[10:13] offset:18432
	s_waitcnt vmcnt(14)
	ds_write_b128 v152, v[14:17] offset:27648
	s_waitcnt vmcnt(13)
	ds_write_b128 v152, v[18:21] offset:36864
	s_waitcnt vmcnt(12)
	ds_write_b128 v152, v[22:25] offset:46080
	s_waitcnt lgkmcnt(0)
	s_barrier
	global_load_dwordx4 v[96:99], v[54:55], off offset:384
	global_load_dwordx4 v[100:103], v[56:57], off offset:384
	global_load_dwordx4 v[104:107], v[50:51], off offset:384
	global_load_dwordx4 v[108:111], v[52:53], off offset:384
	global_load_dwordx4 v[112:115], v[58:59], off offset:384
	global_load_dwordx4 v[116:119], v[60:61], off offset:384
	v_and_b32_e32 v2, 31, v62
	v_lshrrev_b32_e32 v3, 1, v62
	v_and_or_b32 v4, v3, s24, v2
	v_and_b32_e32 v2, 16, v3
	v_and_b32_e32 v3, 0x5f, v62
	v_mad_u32_u24 v66, v3, s23, v2
	v_add_u32_e32 v71, 0x12000, v66
	s_waitcnt vmcnt(17)
	ds_write_b128 v153, v[26:29]
	s_waitcnt vmcnt(16)
	ds_write_b128 v153, v[30:33] offset:9216
	s_waitcnt vmcnt(13)
	ds_write_b128 v153, v[38:41] offset:18432
	ds_write_b128 v153, v[34:37] offset:27648
	s_waitcnt vmcnt(10)
	ds_write_b128 v153, v[42:45] offset:36864
	s_waitcnt vmcnt(7)
	ds_write_b128 v153, v[46:49] offset:46080
	v_mad_u64_u32 v[154:155], s[0:1], v4, s23, v[2:3]
	ds_read_b128 v[2:5], v66 offset:36864
	ds_read_b128 v[120:123], v66 offset:36896
	ds_read_b128 v[6:9], v66 offset:41472
	ds_read_b128 v[124:127], v66 offset:41504
	ds_read_b128 v[10:13], v154
	ds_read_b128 v[128:131], v154 offset:32
	ds_read_b128 v[14:17], v154 offset:4608
	ds_read_b128 v[132:135], v154 offset:4640
	s_setprio 1
	s_waitcnt lgkmcnt(3)
	v_mfma_f32_32x32x16_bf16 v[50:65], v[10:13], v[2:5], 0
	v_mfma_f32_32x32x16_bf16 v[18:33], v[10:13], v[6:9], 0
	s_waitcnt lgkmcnt(1)
	v_mfma_f32_32x32x16_bf16 v[34:49], v[14:17], v[2:5], 0
	v_mfma_f32_32x32x16_bf16 v[2:17], v[14:17], v[6:9], 0
	s_setprio 0
	ds_read_b128 v[136:139], v66 offset:36928
	ds_read_b128 v[140:143], v66 offset:41536
	ds_read_b128 v[144:147], v154 offset:64
	ds_read_b128 v[148:151], v154 offset:4672
	s_setprio 1
	s_waitcnt lgkmcnt(4)
	v_mfma_f32_32x32x16_bf16 v[2:17], v[132:135], v[124:127], v[2:17]
	v_mfma_f32_32x32x16_bf16 v[50:65], v[128:131], v[120:123], v[50:65]
	v_mfma_f32_32x32x16_bf16 v[18:33], v[128:131], v[124:127], v[18:33]
	v_mfma_f32_32x32x16_bf16 v[34:49], v[132:135], v[120:123], v[34:49]
	s_setprio 0
	ds_read_b128 v[120:123], v66 offset:36960
	ds_read_b128 v[124:127], v66 offset:41568
	ds_read_b128 v[128:131], v154 offset:96
	ds_read_b128 v[132:135], v154 offset:4704
	s_setprio 1
	s_waitcnt lgkmcnt(4)
	v_mfma_f32_32x32x16_bf16 v[2:17], v[148:151], v[140:143], v[2:17]
	v_mfma_f32_32x32x16_bf16 v[50:65], v[144:147], v[136:139], v[50:65]
	v_mfma_f32_32x32x16_bf16 v[18:33], v[144:147], v[140:143], v[18:33]
	v_mfma_f32_32x32x16_bf16 v[34:49], v[148:151], v[136:139], v[34:49]
	s_setprio 0
	s_setprio 1
	s_waitcnt lgkmcnt(0)
	v_mfma_f32_32x32x16_bf16 v[2:17], v[132:135], v[124:127], v[2:17]
	v_mfma_f32_32x32x16_bf16 v[50:65], v[128:131], v[120:123], v[50:65]
	v_mfma_f32_32x32x16_bf16 v[18:33], v[128:131], v[124:127], v[18:33]
	v_mfma_f32_32x32x16_bf16 v[34:49], v[132:135], v[120:123], v[34:49]
	s_setprio 0
	s_barrier
	ds_write_b128 v152, v[80:83]
	ds_write_b128 v152, v[72:75] offset:9216
	ds_write_b128 v152, v[76:79] offset:18432
	ds_write_b128 v152, v[88:91] offset:27648
	ds_write_b128 v152, v[84:87] offset:36864
	s_waitcnt vmcnt(6)
	ds_write_b128 v152, v[92:95] offset:46080
	v_add_u32_e32 v128, 0x12000, v154
	ds_read_b128 v[72:75], v71 offset:36864
	ds_read_b128 v[76:79], v71 offset:36896
	ds_read_b128 v[80:83], v71 offset:41472
	ds_read_b128 v[84:87], v71 offset:41504
	ds_read_b128 v[88:91], v128
	ds_read_b128 v[92:95], v128 offset:32
	ds_read_b128 v[120:123], v128 offset:4608
	ds_read_b128 v[124:127], v128 offset:4640
	s_setprio 1
	s_waitcnt lgkmcnt(1)
	v_mfma_f32_32x32x16_bf16 v[2:17], v[120:123], v[80:83], v[2:17]
	v_mfma_f32_32x32x16_bf16 v[50:65], v[88:91], v[72:75], v[50:65]
	v_mfma_f32_32x32x16_bf16 v[18:33], v[88:91], v[80:83], v[18:33]
	v_mfma_f32_32x32x16_bf16 v[34:49], v[120:123], v[72:75], v[34:49]
	s_setprio 0
	ds_read_b128 v[72:75], v71 offset:36928
	ds_read_b128 v[80:83], v71 offset:41536
	ds_read_b128 v[88:91], v128 offset:64
	ds_read_b128 v[120:123], v128 offset:4672
	s_setprio 1
	s_waitcnt lgkmcnt(4)
	v_mfma_f32_32x32x16_bf16 v[2:17], v[124:127], v[84:87], v[2:17]
	v_mfma_f32_32x32x16_bf16 v[50:65], v[92:95], v[76:79], v[50:65]
	v_mfma_f32_32x32x16_bf16 v[18:33], v[92:95], v[84:87], v[18:33]
	v_mfma_f32_32x32x16_bf16 v[34:49], v[124:127], v[76:79], v[34:49]
	s_setprio 0
	ds_read_b128 v[76:79], v71 offset:36960
	ds_read_b128 v[84:87], v71 offset:41568
	ds_read_b128 v[92:95], v128 offset:96
	ds_read_b128 v[124:127], v128 offset:4704
	s_setprio 1
	s_waitcnt lgkmcnt(4)
	v_mfma_f32_32x32x16_bf16 v[2:17], v[120:123], v[80:83], v[2:17]
	v_mfma_f32_32x32x16_bf16 v[50:65], v[88:91], v[72:75], v[50:65]
	v_mfma_f32_32x32x16_bf16 v[18:33], v[88:91], v[80:83], v[18:33]
	v_mfma_f32_32x32x16_bf16 v[34:49], v[120:123], v[72:75], v[34:49]
	s_setprio 0
	s_setprio 1
	s_waitcnt lgkmcnt(0)
	v_mfma_f32_32x32x16_bf16 v[2:17], v[124:127], v[84:87], v[2:17]
	v_mfma_f32_32x32x16_bf16 v[50:65], v[92:95], v[76:79], v[50:65]
	v_mfma_f32_32x32x16_bf16 v[18:33], v[92:95], v[84:87], v[18:33]
	v_mfma_f32_32x32x16_bf16 v[34:49], v[124:127], v[76:79], v[34:49]
	s_setprio 0
	s_barrier
	s_waitcnt vmcnt(3)
	ds_write_b128 v153, v[104:107]
	ds_write_b128 v153, v[96:99] offset:9216
	ds_write_b128 v153, v[100:103] offset:18432
	s_waitcnt vmcnt(1)
	ds_write_b128 v153, v[112:115] offset:27648
	ds_write_b128 v153, v[108:111] offset:36864
	s_waitcnt vmcnt(0)
	ds_write_b128 v153, v[116:119] offset:46080
	ds_read_b128 v[72:75], v66 offset:36864
	ds_read_b128 v[76:79], v66 offset:36896
	ds_read_b128 v[80:83], v66 offset:41472
	ds_read_b128 v[84:87], v66 offset:41504
	ds_read_b128 v[88:91], v154
	ds_read_b128 v[92:95], v154 offset:32
	ds_read_b128 v[96:99], v154 offset:4608
	ds_read_b128 v[100:103], v154 offset:4640
	s_setprio 1
	s_waitcnt lgkmcnt(1)
	v_mfma_f32_32x32x16_bf16 v[2:17], v[96:99], v[80:83], v[2:17]
	v_mfma_f32_32x32x16_bf16 v[50:65], v[88:91], v[72:75], v[50:65]
	v_mfma_f32_32x32x16_bf16 v[18:33], v[88:91], v[80:83], v[18:33]
	v_mfma_f32_32x32x16_bf16 v[34:49], v[96:99], v[72:75], v[34:49]
	s_setprio 0
	ds_read_b128 v[72:75], v66 offset:36928
	ds_read_b128 v[80:83], v66 offset:41536
	ds_read_b128 v[88:91], v154 offset:64
	ds_read_b128 v[96:99], v154 offset:4672
	s_setprio 1
	s_waitcnt lgkmcnt(4)
	v_mfma_f32_32x32x16_bf16 v[2:17], v[100:103], v[84:87], v[2:17]
	v_mfma_f32_32x32x16_bf16 v[50:65], v[92:95], v[76:79], v[50:65]
	v_mfma_f32_32x32x16_bf16 v[18:33], v[92:95], v[84:87], v[18:33]
	v_mfma_f32_32x32x16_bf16 v[34:49], v[100:103], v[76:79], v[34:49]
	s_setprio 0
	ds_read_b128 v[76:79], v66 offset:36960
	ds_read_b128 v[84:87], v66 offset:41568
	ds_read_b128 v[92:95], v154 offset:96
	ds_read_b128 v[100:103], v154 offset:4704
	s_setprio 1
	s_waitcnt lgkmcnt(4)
	v_mfma_f32_32x32x16_bf16 v[2:17], v[96:99], v[80:83], v[2:17]
	v_mfma_f32_32x32x16_bf16 v[50:65], v[88:91], v[72:75], v[50:65]
	v_mfma_f32_32x32x16_bf16 v[18:33], v[88:91], v[80:83], v[18:33]
	v_mfma_f32_32x32x16_bf16 v[34:49], v[96:99], v[72:75], v[34:49]
	s_setprio 0
	s_setprio 1
	s_waitcnt lgkmcnt(0)
	v_mfma_f32_32x32x16_bf16 v[2:17], v[100:103], v[84:87], v[2:17]
	v_mfma_f32_32x32x16_bf16 v[50:65], v[92:95], v[76:79], v[50:65]
	v_mfma_f32_32x32x16_bf16 v[18:33], v[92:95], v[84:87], v[18:33]
	v_mfma_f32_32x32x16_bf16 v[34:49], v[100:103], v[76:79], v[34:49]
	s_setprio 0
	s_barrier
	ds_read_b128 v[72:75], v71 offset:36864
	ds_read_b128 v[76:79], v71 offset:36896
	ds_read_b128 v[80:83], v71 offset:41472
	ds_read_b128 v[84:87], v71 offset:41504
	ds_read_b128 v[88:91], v128
	ds_read_b128 v[92:95], v128 offset:32
	ds_read_b128 v[96:99], v128 offset:4608
	ds_read_b128 v[100:103], v128 offset:4640
	s_setprio 1
	s_waitcnt lgkmcnt(1)
	v_mfma_f32_32x32x16_bf16 v[2:17], v[96:99], v[80:83], v[2:17]
	v_mfma_f32_32x32x16_bf16 v[50:65], v[88:91], v[72:75], v[50:65]
	v_mfma_f32_32x32x16_bf16 v[18:33], v[88:91], v[80:83], v[18:33]
	v_mfma_f32_32x32x16_bf16 v[34:49], v[96:99], v[72:75], v[34:49]
	s_setprio 0
	ds_read_b128 v[72:75], v71 offset:36928
	ds_read_b128 v[80:83], v71 offset:41536
	ds_read_b128 v[88:91], v128 offset:64
	ds_read_b128 v[96:99], v128 offset:4672
	s_setprio 1
	s_waitcnt lgkmcnt(4)
	v_mfma_f32_32x32x16_bf16 v[2:17], v[100:103], v[84:87], v[2:17]
	v_mfma_f32_32x32x16_bf16 v[50:65], v[92:95], v[76:79], v[50:65]
	v_mfma_f32_32x32x16_bf16 v[18:33], v[92:95], v[84:87], v[18:33]
	v_mfma_f32_32x32x16_bf16 v[34:49], v[100:103], v[76:79], v[34:49]
	s_setprio 0
	ds_read_b128 v[76:79], v71 offset:36960
	ds_read_b128 v[84:87], v71 offset:41568
	ds_read_b128 v[92:95], v128 offset:96
	ds_read_b128 v[100:103], v128 offset:4704
	s_setprio 1
	s_waitcnt lgkmcnt(4)
	v_mfma_f32_32x32x16_bf16 v[2:17], v[96:99], v[80:83], v[2:17]
	v_mfma_f32_32x32x16_bf16 v[50:65], v[88:91], v[72:75], v[50:65]
	v_mfma_f32_32x32x16_bf16 v[18:33], v[88:91], v[80:83], v[18:33]
	v_mfma_f32_32x32x16_bf16 v[34:49], v[96:99], v[72:75], v[34:49]
	s_setprio 0
	s_setprio 1
	s_waitcnt lgkmcnt(0)
	v_mfma_f32_32x32x16_bf16 v[2:17], v[100:103], v[84:87], v[2:17]
	v_mfma_f32_32x32x16_bf16 v[50:65], v[92:95], v[76:79], v[50:65]
	v_mfma_f32_32x32x16_bf16 v[18:33], v[92:95], v[84:87], v[18:33]
	v_mfma_f32_32x32x16_bf16 v[34:49], v[100:103], v[76:79], v[34:49]
	s_setprio 0
	v_readlane_b32 s40, v245, 0
	v_lshrrev_b32_e32 v71, 1, v69
	v_readlane_b32 s54, v245, 14
	v_readlane_b32 s55, v245, 15
	v_and_b32_e32 v66, 0x5f, v69
	v_lshlrev_b32_e32 v69, 1, v69
	v_and_b32_e32 v71, 16, v71
	s_lshl_b32 s0, s38, 2
	s_mov_b64 s[18:19], s[54:55]
	v_and_or_b32 v69, v69, s29, v71
	s_add_u32 s0, s18, s0
	v_mad_u32_u24 v66, v66, s30, v69
	s_addc_u32 s1, s19, 0
	v_mov_b32_e32 v69, v67
	v_lshl_add_u32 v208, v70, 4, s15
	v_ashrrev_i32_e32 v209, 31, v208
	v_lshlrev_b64 v[208:209], 11, v[208:209]
	v_lshlrev_b32_e32 v210, 3, v1
	v_or3_b32 v208, v208, s14, v210
	v_lshl_add_u64 v[208:209], s[96:97], 0, v[208:209]
	s_mov_b64 s[98:99], 0x73a1000
	v_lshl_add_u64 v[208:209], v[208:209], 0, s[98:99]
	s_mov_b64 s[98:99], 0x2000
	global_load_dwordx2 v[176:177], v[208:209], off offset:-4096
	global_load_dwordx2 v[178:179], v[208:209], off offset:-2048
	global_load_dwordx2 v[180:181], v[208:209], off
	global_load_dwordx2 v[182:183], v[208:209], off offset:2048
	v_lshl_add_u64 v[208:209], v[208:209], 0, s[98:99]
	global_load_dwordx2 v[184:185], v[208:209], off offset:-4096
	global_load_dwordx2 v[186:187], v[208:209], off offset:-2048
	global_load_dwordx2 v[188:189], v[208:209], off
	global_load_dwordx2 v[190:191], v[208:209], off offset:2048
	v_lshl_add_u64 v[208:209], v[208:209], 0, s[98:99]
	global_load_dwordx2 v[192:193], v[208:209], off offset:-4096
	global_load_dwordx2 v[194:195], v[208:209], off offset:-2048
	global_load_dwordx2 v[196:197], v[208:209], off
	global_load_dwordx2 v[198:199], v[208:209], off offset:2048
	v_lshl_add_u64 v[208:209], v[208:209], 0, s[98:99]
	global_load_dwordx2 v[200:201], v[208:209], off offset:-4096
	global_load_dwordx2 v[202:203], v[208:209], off offset:-2048
	global_load_dwordx2 v[204:205], v[208:209], off
	global_load_dwordx2 v[206:207], v[208:209], off offset:2048
	s_barrier
	ds_write_b128 v66, v[50:53]
	ds_write_b128 v66, v[54:57] offset:32
	ds_write_b128 v66, v[58:61] offset:64
	ds_write_b128 v66, v[62:65] offset:96
	ds_write_b128 v66, v[34:37] offset:128
	ds_write_b128 v66, v[38:41] offset:160
	ds_write_b128 v66, v[42:45] offset:192
	ds_write_b128 v66, v[46:49] offset:224
	ds_write_b128 v66, v[18:21] offset:33280
	ds_write_b128 v66, v[22:25] offset:33312
	ds_write_b128 v66, v[26:29] offset:33344
	ds_write_b128 v66, v[30:33] offset:33376
	ds_write_b128 v66, v[2:5] offset:33408
	ds_write_b128 v66, v[6:9] offset:33440
	ds_write_b128 v66, v[10:13] offset:33472
	ds_write_b128 v66, v[14:17] offset:33504
	v_lshl_add_u64 v[2:3], v[68:69], 2, s[0:1]
	s_waitcnt lgkmcnt(0)
	s_barrier
	global_load_dwordx4 v[2:5], v[2:3], off
	v_mul_lo_u32 v6, v70, s31
	v_lshl_add_u32 v8, v1, 4, v6
	v_lshl_add_u32 v6, v70, 4, s15
	v_ashrrev_i32_e32 v7, 31, v6
	v_lshlrev_b64 v[6:7], 11, v[6:7]
	v_lshlrev_b32_e32 v1, 3, v1
	v_or3_b32 v6, v6, s14, v1
	v_lshl_add_u64 v[6:7], s[96:97], 0, v[6:7]
	s_mov_b64 s[14:15], 0
	v_readlane_b32 s41, v245, 1
	v_readlane_b32 s42, v245, 2
	v_readlane_b32 s43, v245, 3
	v_readlane_b32 s44, v245, 4
	v_readlane_b32 s45, v245, 5
	v_readlane_b32 s46, v245, 6
	v_readlane_b32 s47, v245, 7
	v_readlane_b32 s48, v245, 8
	v_readlane_b32 s49, v245, 9
	v_readlane_b32 s50, v245, 10
	v_readlane_b32 s51, v245, 11
	v_readlane_b32 s52, v245, 12
	v_readlane_b32 s53, v245, 13
.LBB0_809:
	v_lshl_add_u64 v[26:27], v[6:7], 0, s[14:15]
	v_add_co_u32_e32 v10, vcc, 0x73a0000, v26
	v_add_co_u32_e64 v12, s[0:1], s34, v26
	s_nop 0
	v_addc_co_u32_e32 v11, vcc, 0, v27, vcc
	v_addc_co_u32_e64 v13, s[0:1], 0, v27, s[0:1]
	ds_read_b128 v[10:13], v8
	ds_read_b128 v[14:17], v8 offset:1040
	ds_read_b128 v[18:21], v8 offset:2080
	ds_read_b128 v[22:25], v8 offset:3120
	v_add_co_u32_e32 v36, vcc, s33, v26
	s_add_u32 s14, s14, 0x2000
	s_nop 0
	v_addc_co_u32_e32 v37, vcc, 0, v27, vcc
	s_waitcnt vmcnt(0) lgkmcnt(3)
	v_pk_mul_f32 v[10:11], v[2:3], v[10:11]
	v_pk_mul_f32 v[12:13], v[4:5], v[12:13]
	v_add_co_u32_e32 v26, vcc, s35, v26
	s_addc_u32 s15, s15, 0
	s_waitcnt lgkmcnt(2)
	v_pk_mul_f32 v[14:15], v[2:3], v[14:15]
	v_pk_mul_f32 v[16:17], v[4:5], v[16:17]
	s_waitcnt lgkmcnt(1)
	v_pk_mul_f32 v[18:19], v[2:3], v[18:19]
	v_pk_mul_f32 v[20:21], v[4:5], v[20:21]
	s_waitcnt lgkmcnt(0)
	v_pk_mul_f32 v[22:23], v[2:3], v[22:23]
	v_pk_mul_f32 v[24:25], v[4:5], v[24:25]
	v_add_u32_e32 v8, 0x1040, v8
	v_addc_co_u32_e32 v27, vcc, 0, v27, vcc
	s_cmpk_lg_u32 s14, 0x8000
	v_lshlrev_b32_e32 v38, 16, v176
	v_and_b32_e32 v39, 0xffff0000, v176
	v_lshlrev_b32_e32 v176, 16, v177
	v_and_b32_e32 v177, 0xffff0000, v177
	v_lshlrev_b32_e32 v40, 16, v178
	v_and_b32_e32 v41, 0xffff0000, v178
	v_lshlrev_b32_e32 v178, 16, v179
	v_and_b32_e32 v179, 0xffff0000, v179
	v_lshlrev_b32_e32 v42, 16, v180
	v_and_b32_e32 v43, 0xffff0000, v180
	v_lshlrev_b32_e32 v180, 16, v181
	v_and_b32_e32 v181, 0xffff0000, v181
	v_lshlrev_b32_e32 v44, 16, v182
	v_and_b32_e32 v45, 0xffff0000, v182
	v_lshlrev_b32_e32 v182, 16, v183
	v_and_b32_e32 v183, 0xffff0000, v183
	v_pk_mul_f32 v[10:11], v[10:11], v[38:39]
	v_pk_mul_f32 v[12:13], v[12:13], v[176:177]
	v_pk_mul_f32 v[14:15], v[14:15], v[40:41]
	v_pk_mul_f32 v[16:17], v[16:17], v[178:179]
	v_pk_mul_f32 v[18:19], v[18:19], v[42:43]
	v_pk_mul_f32 v[20:21], v[20:21], v[180:181]
	v_pk_mul_f32 v[22:23], v[22:23], v[44:45]
	v_pk_mul_f32 v[24:25], v[24:25], v[182:183]
	v_cvt_pk_bf16_f32 v10, v10, v11
	v_cvt_pk_bf16_f32 v11, v12, v13
	v_cvt_pk_bf16_f32 v12, v14, v15
	v_cvt_pk_bf16_f32 v13, v16, v17
	v_cvt_pk_bf16_f32 v14, v18, v19
	v_cvt_pk_bf16_f32 v15, v20, v21
	v_cvt_pk_bf16_f32 v16, v22, v23
	v_cvt_pk_bf16_f32 v17, v24, v25
	global_store_dwordx2 v[26:27], v[10:11], off offset:-4096
	global_store_dwordx2 v[36:37], v[12:13], off offset:2048
	global_store_dwordx2 v[26:27], v[14:15], off
	global_store_dwordx2 v[26:27], v[16:17], off offset:2048
	v_lshl_add_u64 v[26:27], v[6:7], 0, s[14:15]
	v_add_co_u32_e32 v10, vcc, 0x73a0000, v26
	v_add_co_u32_e64 v12, s[0:1], s34, v26
	s_nop 0
	v_addc_co_u32_e32 v11, vcc, 0, v27, vcc
	v_addc_co_u32_e64 v13, s[0:1], 0, v27, s[0:1]
	ds_read_b128 v[10:13], v8
	ds_read_b128 v[14:17], v8 offset:1040
	ds_read_b128 v[18:21], v8 offset:2080
	ds_read_b128 v[22:25], v8 offset:3120
	v_add_co_u32_e32 v36, vcc, s33, v26
	s_add_u32 s14, s14, 0x2000
	s_nop 0
	v_addc_co_u32_e32 v37, vcc, 0, v27, vcc
	s_waitcnt lgkmcnt(3)
	v_pk_mul_f32 v[10:11], v[2:3], v[10:11]
	v_pk_mul_f32 v[12:13], v[4:5], v[12:13]
	v_add_co_u32_e32 v26, vcc, s35, v26
	s_addc_u32 s15, s15, 0
	s_waitcnt lgkmcnt(2)
	v_pk_mul_f32 v[14:15], v[2:3], v[14:15]
	v_pk_mul_f32 v[16:17], v[4:5], v[16:17]
	s_waitcnt lgkmcnt(1)
	v_pk_mul_f32 v[18:19], v[2:3], v[18:19]
	v_pk_mul_f32 v[20:21], v[4:5], v[20:21]
	s_waitcnt lgkmcnt(0)
	v_pk_mul_f32 v[22:23], v[2:3], v[22:23]
	v_pk_mul_f32 v[24:25], v[4:5], v[24:25]
	v_add_u32_e32 v8, 0x1040, v8
	v_addc_co_u32_e32 v27, vcc, 0, v27, vcc
	s_cmpk_lg_u32 s14, 0x8000
	v_lshlrev_b32_e32 v38, 16, v184
	v_and_b32_e32 v39, 0xffff0000, v184
	v_lshlrev_b32_e32 v184, 16, v185
	v_and_b32_e32 v185, 0xffff0000, v185
	v_lshlrev_b32_e32 v40, 16, v186
	v_and_b32_e32 v41, 0xffff0000, v186
	v_lshlrev_b32_e32 v186, 16, v187
	v_and_b32_e32 v187, 0xffff0000, v187
	v_lshlrev_b32_e32 v42, 16, v188
	v_and_b32_e32 v43, 0xffff0000, v188
	v_lshlrev_b32_e32 v188, 16, v189
	v_and_b32_e32 v189, 0xffff0000, v189
	v_lshlrev_b32_e32 v44, 16, v190
	v_and_b32_e32 v45, 0xffff0000, v190
	v_lshlrev_b32_e32 v190, 16, v191
	v_and_b32_e32 v191, 0xffff0000, v191
	v_pk_mul_f32 v[10:11], v[10:11], v[38:39]
	v_pk_mul_f32 v[12:13], v[12:13], v[184:185]
	v_pk_mul_f32 v[14:15], v[14:15], v[40:41]
	v_pk_mul_f32 v[16:17], v[16:17], v[186:187]
	v_pk_mul_f32 v[18:19], v[18:19], v[42:43]
	v_pk_mul_f32 v[20:21], v[20:21], v[188:189]
	v_pk_mul_f32 v[22:23], v[22:23], v[44:45]
	v_pk_mul_f32 v[24:25], v[24:25], v[190:191]
	v_cvt_pk_bf16_f32 v10, v10, v11
	v_cvt_pk_bf16_f32 v11, v12, v13
	v_cvt_pk_bf16_f32 v12, v14, v15
	v_cvt_pk_bf16_f32 v13, v16, v17
	v_cvt_pk_bf16_f32 v14, v18, v19
	v_cvt_pk_bf16_f32 v15, v20, v21
	v_cvt_pk_bf16_f32 v16, v22, v23
	v_cvt_pk_bf16_f32 v17, v24, v25
	global_store_dwordx2 v[26:27], v[10:11], off offset:-4096
	global_store_dwordx2 v[36:37], v[12:13], off offset:2048
	global_store_dwordx2 v[26:27], v[14:15], off
	global_store_dwordx2 v[26:27], v[16:17], off offset:2048
	v_lshl_add_u64 v[26:27], v[6:7], 0, s[14:15]
	v_add_co_u32_e32 v10, vcc, 0x73a0000, v26
	v_add_co_u32_e64 v12, s[0:1], s34, v26
	s_nop 0
	v_addc_co_u32_e32 v11, vcc, 0, v27, vcc
	v_addc_co_u32_e64 v13, s[0:1], 0, v27, s[0:1]
	ds_read_b128 v[10:13], v8
	ds_read_b128 v[14:17], v8 offset:1040
	ds_read_b128 v[18:21], v8 offset:2080
	ds_read_b128 v[22:25], v8 offset:3120
	v_add_co_u32_e32 v36, vcc, s33, v26
	s_add_u32 s14, s14, 0x2000
	s_nop 0
	v_addc_co_u32_e32 v37, vcc, 0, v27, vcc
	s_waitcnt lgkmcnt(3)
	v_pk_mul_f32 v[10:11], v[2:3], v[10:11]
	v_pk_mul_f32 v[12:13], v[4:5], v[12:13]
	v_add_co_u32_e32 v26, vcc, s35, v26
	s_addc_u32 s15, s15, 0
	s_waitcnt lgkmcnt(2)
	v_pk_mul_f32 v[14:15], v[2:3], v[14:15]
	v_pk_mul_f32 v[16:17], v[4:5], v[16:17]
	s_waitcnt lgkmcnt(1)
	v_pk_mul_f32 v[18:19], v[2:3], v[18:19]
	v_pk_mul_f32 v[20:21], v[4:5], v[20:21]
	s_waitcnt lgkmcnt(0)
	v_pk_mul_f32 v[22:23], v[2:3], v[22:23]
	v_pk_mul_f32 v[24:25], v[4:5], v[24:25]
	v_add_u32_e32 v8, 0x1040, v8
	v_addc_co_u32_e32 v27, vcc, 0, v27, vcc
	s_cmpk_lg_u32 s14, 0x8000
	v_lshlrev_b32_e32 v38, 16, v192
	v_and_b32_e32 v39, 0xffff0000, v192
	v_lshlrev_b32_e32 v192, 16, v193
	v_and_b32_e32 v193, 0xffff0000, v193
	v_lshlrev_b32_e32 v40, 16, v194
	v_and_b32_e32 v41, 0xffff0000, v194
	v_lshlrev_b32_e32 v194, 16, v195
	v_and_b32_e32 v195, 0xffff0000, v195
	v_lshlrev_b32_e32 v42, 16, v196
	v_and_b32_e32 v43, 0xffff0000, v196
	v_lshlrev_b32_e32 v196, 16, v197
	v_and_b32_e32 v197, 0xffff0000, v197
	v_lshlrev_b32_e32 v44, 16, v198
	v_and_b32_e32 v45, 0xffff0000, v198
	v_lshlrev_b32_e32 v198, 16, v199
	v_and_b32_e32 v199, 0xffff0000, v199
	v_pk_mul_f32 v[10:11], v[10:11], v[38:39]
	v_pk_mul_f32 v[12:13], v[12:13], v[192:193]
	v_pk_mul_f32 v[14:15], v[14:15], v[40:41]
	v_pk_mul_f32 v[16:17], v[16:17], v[194:195]
	v_pk_mul_f32 v[18:19], v[18:19], v[42:43]
	v_pk_mul_f32 v[20:21], v[20:21], v[196:197]
	v_pk_mul_f32 v[22:23], v[22:23], v[44:45]
	v_pk_mul_f32 v[24:25], v[24:25], v[198:199]
	v_cvt_pk_bf16_f32 v10, v10, v11
	v_cvt_pk_bf16_f32 v11, v12, v13
	v_cvt_pk_bf16_f32 v12, v14, v15
	v_cvt_pk_bf16_f32 v13, v16, v17
	v_cvt_pk_bf16_f32 v14, v18, v19
	v_cvt_pk_bf16_f32 v15, v20, v21
	v_cvt_pk_bf16_f32 v16, v22, v23
	v_cvt_pk_bf16_f32 v17, v24, v25
	global_store_dwordx2 v[26:27], v[10:11], off offset:-4096
	global_store_dwordx2 v[36:37], v[12:13], off offset:2048
	global_store_dwordx2 v[26:27], v[14:15], off
	global_store_dwordx2 v[26:27], v[16:17], off offset:2048
	v_lshl_add_u64 v[26:27], v[6:7], 0, s[14:15]
	v_add_co_u32_e32 v10, vcc, 0x73a0000, v26
	v_add_co_u32_e64 v12, s[0:1], s34, v26
	s_nop 0
	v_addc_co_u32_e32 v11, vcc, 0, v27, vcc
	v_addc_co_u32_e64 v13, s[0:1], 0, v27, s[0:1]
	ds_read_b128 v[10:13], v8
	ds_read_b128 v[14:17], v8 offset:1040
	ds_read_b128 v[18:21], v8 offset:2080
	ds_read_b128 v[22:25], v8 offset:3120
	v_add_co_u32_e32 v36, vcc, s33, v26
	s_add_u32 s14, s14, 0x2000
	s_nop 0
	v_addc_co_u32_e32 v37, vcc, 0, v27, vcc
	s_waitcnt lgkmcnt(3)
	v_pk_mul_f32 v[10:11], v[2:3], v[10:11]
	v_pk_mul_f32 v[12:13], v[4:5], v[12:13]
	v_add_co_u32_e32 v26, vcc, s35, v26
	s_addc_u32 s15, s15, 0
	s_waitcnt lgkmcnt(2)
	v_pk_mul_f32 v[14:15], v[2:3], v[14:15]
	v_pk_mul_f32 v[16:17], v[4:5], v[16:17]
	s_waitcnt lgkmcnt(1)
	v_pk_mul_f32 v[18:19], v[2:3], v[18:19]
	v_pk_mul_f32 v[20:21], v[4:5], v[20:21]
	s_waitcnt lgkmcnt(0)
	v_pk_mul_f32 v[22:23], v[2:3], v[22:23]
	v_pk_mul_f32 v[24:25], v[4:5], v[24:25]
	v_add_u32_e32 v8, 0x1040, v8
	v_addc_co_u32_e32 v27, vcc, 0, v27, vcc
	s_cmpk_lg_u32 s14, 0x8000
	v_lshlrev_b32_e32 v38, 16, v200
	v_and_b32_e32 v39, 0xffff0000, v200
	v_lshlrev_b32_e32 v200, 16, v201
	v_and_b32_e32 v201, 0xffff0000, v201
	v_lshlrev_b32_e32 v40, 16, v202
	v_and_b32_e32 v41, 0xffff0000, v202
	v_lshlrev_b32_e32 v202, 16, v203
	v_and_b32_e32 v203, 0xffff0000, v203
	v_lshlrev_b32_e32 v42, 16, v204
	v_and_b32_e32 v43, 0xffff0000, v204
	v_lshlrev_b32_e32 v204, 16, v205
	v_and_b32_e32 v205, 0xffff0000, v205
	v_lshlrev_b32_e32 v44, 16, v206
	v_and_b32_e32 v45, 0xffff0000, v206
	v_lshlrev_b32_e32 v206, 16, v207
	v_and_b32_e32 v207, 0xffff0000, v207
	v_pk_mul_f32 v[10:11], v[10:11], v[38:39]
	v_pk_mul_f32 v[12:13], v[12:13], v[200:201]
	v_pk_mul_f32 v[14:15], v[14:15], v[40:41]
	v_pk_mul_f32 v[16:17], v[16:17], v[202:203]
	v_pk_mul_f32 v[18:19], v[18:19], v[42:43]
	v_pk_mul_f32 v[20:21], v[20:21], v[204:205]
	v_pk_mul_f32 v[22:23], v[22:23], v[44:45]
	v_pk_mul_f32 v[24:25], v[24:25], v[206:207]
	v_cvt_pk_bf16_f32 v10, v10, v11
	v_cvt_pk_bf16_f32 v11, v12, v13
	v_cvt_pk_bf16_f32 v12, v14, v15
	v_cvt_pk_bf16_f32 v13, v16, v17
	v_cvt_pk_bf16_f32 v14, v18, v19
	v_cvt_pk_bf16_f32 v15, v20, v21
	v_cvt_pk_bf16_f32 v16, v22, v23
	v_cvt_pk_bf16_f32 v17, v24, v25
	global_store_dwordx2 v[26:27], v[10:11], off offset:-4096
	global_store_dwordx2 v[36:37], v[12:13], off offset:2048
	global_store_dwordx2 v[26:27], v[14:15], off
	global_store_dwordx2 v[26:27], v[16:17], off offset:2048
	s_add_i32 s37, s37, s62
	s_add_i32 s21, s21, s22
	s_add_i32 s36, s36, s62
	s_cmpk_lt_i32 s37, 0x300
	s_cbranch_scc1 .LBB0_794
